# down-GEMM EpiResid epilogue: bf16 residual unpack batched behind one vmcnt(0) per row-iteration instead of a wait after every load
# speedup vs baseline: 1.1276x; 1.0006x over previous
.LBB0_104:
	s_and_b64 vcc, exec, s[4:5]
	s_cbranch_vccnz .Lresid_f32_7
	s_waitcnt vmcnt(0)
	v_lshlrev_b32_e32 v14, 16, v16
	v_and_b32_e32 v15, 0xffff0000, v16
	v_lshlrev_b32_e32 v16, 16, v17
	v_and_b32_e32 v17, 0xffff0000, v17
	v_lshlrev_b32_e32 v22, 16, v24
	v_and_b32_e32 v23, 0xffff0000, v24
	v_lshlrev_b32_e32 v24, 16, v25
	v_and_b32_e32 v25, 0xffff0000, v25

.LBB0_111:
	s_or_b64 exec, exec, s[0:1]
	v_or_b32_e32 v0, s8, v84
	v_lshl_add_u32 v84, v83, 6, v0
	v_lshlrev_b32_e32 v0, 5, v85
	v_lshlrev_b32_e32 v66, 2, v86
	v_or3_b32 v82, v0, v66, s4
	v_add_u32_e32 v0, 0xfffff000, v84
	v_lshrrev_b32_e32 v66, 11, v0
	s_movk_i32 s0, 0x1000
	v_add_u32_e32 v66, 1, v66
	v_cmp_gt_i32_e32 vcc, s0, v84
	v_ashrrev_i32_e32 v83, 31, v82
	v_ashrrev_i32_e32 v85, 31, v84
	v_cndmask_b32_e64 v68, v66, 0, vcc
	v_mov_b64_e32 v[66:67], s[6:7]
	v_mad_u64_u32 v[66:67], s[0:1], v68, s65, v[66:67]
	v_lshl_add_u64 v[74:75], v[82:83], 2, v[66:67]
	global_load_dwordx4 v[66:69], v[74:75], off
	v_cndmask_b32_e32 v70, v0, v84, vcc
	v_mov_b32_e32 v0, s64
	v_mov_b32_e32 v72, s96
	v_cndmask_b32_e32 v71, 0, v85, vcc
	v_cndmask_b32_e32 v73, v0, v72, vcc
	v_mov_b32_e32 v0, s62
	v_mov_b32_e32 v72, s66
	v_cndmask_b32_e32 v72, v0, v72, vcc
	v_lshlrev_b64 v[76:77], 12, v[70:71]
	v_lshl_add_u64 v[78:79], v[72:73], 0, v[76:77]
	v_cndmask_b32_e64 v0, 0, 1, s[70:71]
	s_mov_b64 s[0:1], -1
	v_cmp_ne_u32_e64 s[4:5], 1, v0
	s_andn2_b64 vcc, exec, s[70:71]
	v_lshl_add_u64 v[86:87], v[82:83], 1, v[78:79]
	s_cbranch_vccnz .LBB0_113
	global_load_dwordx2 v[72:73], v[86:87], off
	v_lshl_add_u64 v[76:77], v[78:79], 0, v[76:77]
	v_lshl_add_u64 v[88:89], v[82:83], 2, v[76:77]
	s_cbranch_execnz .LBB0_115
	s_branch .LBB0_114

.LBB0_115:
	s_nop 0
	global_load_dwordx4 v[74:77], v[74:75], off offset:64
	s_and_b64 vcc, exec, s[4:5]
	s_mov_b64 s[0:1], -1
	s_cbranch_vccnz .LBB0_117
	global_load_dwordx2 v[80:81], v[86:87], off offset:32
	s_cbranch_execz .LBB0_118
	s_branch .LBB0_119

.LBB0_119:
	s_and_b64 vcc, exec, s[4:5]
	s_cbranch_vccnz .Lresid_f32_0
	s_waitcnt vmcnt(0)
	v_lshlrev_b32_e32 v70, 16, v72
	v_and_b32_e32 v71, 0xffff0000, v72
	v_lshlrev_b32_e32 v72, 16, v73
	v_and_b32_e32 v73, 0xffff0000, v73
	v_lshlrev_b32_e32 v78, 16, v80
	v_and_b32_e32 v79, 0xffff0000, v80
	v_lshlrev_b32_e32 v80, 16, v81
	v_and_b32_e32 v81, 0xffff0000, v81
.Lresid_f32_0:
	v_lshlrev_b64 v[86:87], 12, v[84:85]
	v_pk_add_f32 v[64:65], v[64:65], 0 op_sel_hi:[1,0]
	v_pk_add_f32 v[62:63], v[62:63], 0 op_sel_hi:[1,0]
	v_pk_add_f32 v[60:61], v[60:61], 0 op_sel_hi:[1,0]
	v_pk_add_f32 v[58:59], v[58:59], 0 op_sel_hi:[1,0]
	v_lshl_add_u64 v[86:87], s[22:23], 0, v[86:87]
	s_waitcnt vmcnt(1)
	v_pk_fma_f32 v[64:65], v[64:65], v[68:69], v[72:73]
	v_pk_fma_f32 v[62:63], v[62:63], v[66:67], v[70:71]
	s_waitcnt vmcnt(0)
	v_pk_fma_f32 v[60:61], v[60:61], v[76:77], v[80:81]
	v_pk_fma_f32 v[58:59], v[58:59], v[74:75], v[78:79]
	v_cvt_pk_bf16_f32 v62, v62, v63
	v_cvt_pk_bf16_f32 v63, v64, v65
	v_lshl_add_u64 v[64:65], v[82:83], 1, v[86:87]
	v_cvt_pk_bf16_f32 v58, v58, v59
	v_cvt_pk_bf16_f32 v59, v60, v61
	v_add_u32_e32 v0, 0xfffff010, v84
	global_store_dwordx2 v[64:65], v[58:59], off offset:32
	v_or_b32_e32 v74, 16, v84
	v_lshrrev_b32_e32 v58, 11, v0
	s_movk_i32 s0, 0x1000
	v_add_u32_e32 v58, 1, v58
	v_cmp_gt_i32_e32 vcc, s0, v74
	global_store_dwordx2 v[64:65], v[62:63], off
	v_ashrrev_i32_e32 v75, 31, v74
	v_cndmask_b32_e64 v60, v58, 0, vcc
	v_mov_b64_e32 v[58:59], s[6:7]
	v_mad_u64_u32 v[58:59], s[0:1], v60, s65, v[58:59]
	v_lshl_add_u64 v[66:67], v[82:83], 2, v[58:59]
	global_load_dwordx4 v[58:61], v[66:67], off
	v_cndmask_b32_e32 v62, v0, v74, vcc
	v_mov_b32_e32 v0, s64
	v_mov_b32_e32 v64, s96
	v_cndmask_b32_e32 v63, 0, v75, vcc
	v_cndmask_b32_e32 v65, v0, v64, vcc
	v_mov_b32_e32 v0, s62
	v_mov_b32_e32 v64, s66
	v_cndmask_b32_e32 v64, v0, v64, vcc
	v_lshlrev_b64 v[68:69], 12, v[62:63]
	v_lshl_add_u64 v[70:71], v[64:65], 0, v[68:69]
	s_mov_b64 s[0:1], -1
	s_and_b64 vcc, exec, s[4:5]
	v_lshl_add_u64 v[76:77], v[82:83], 1, v[70:71]
	s_cbranch_vccnz .LBB0_121
	global_load_dwordx2 v[64:65], v[76:77], off
	v_lshl_add_u64 v[68:69], v[70:71], 0, v[68:69]
	v_lshl_add_u64 v[78:79], v[82:83], 2, v[68:69]
	s_cbranch_execnz .LBB0_123
	s_branch .LBB0_122

.LBB0_123:
	s_nop 0
	global_load_dwordx4 v[66:69], v[66:67], off offset:64
	s_and_b64 vcc, exec, s[4:5]
	s_mov_b64 s[0:1], -1
	s_cbranch_vccnz .LBB0_125
	global_load_dwordx2 v[72:73], v[76:77], off offset:32
	s_cbranch_execz .LBB0_126
	s_branch .LBB0_127

.LBB0_127:
	s_and_b64 vcc, exec, s[4:5]
	s_cbranch_vccnz .Lresid_f32_1
	s_waitcnt vmcnt(0)
	v_lshlrev_b32_e32 v62, 16, v64
	v_and_b32_e32 v63, 0xffff0000, v64
	v_lshlrev_b32_e32 v64, 16, v65
	v_and_b32_e32 v65, 0xffff0000, v65
	v_lshlrev_b32_e32 v70, 16, v72
	v_and_b32_e32 v71, 0xffff0000, v72
	v_lshlrev_b32_e32 v72, 16, v73
	v_and_b32_e32 v73, 0xffff0000, v73
.Lresid_f32_1:
	v_lshlrev_b64 v[74:75], 12, v[74:75]
	v_pk_add_f32 v[56:57], v[56:57], 0 op_sel_hi:[1,0]
	v_pk_add_f32 v[54:55], v[54:55], 0 op_sel_hi:[1,0]
	v_pk_add_f32 v[52:53], v[52:53], 0 op_sel_hi:[1,0]
	v_pk_add_f32 v[50:51], v[50:51], 0 op_sel_hi:[1,0]
	v_lshl_add_u64 v[74:75], s[22:23], 0, v[74:75]
	s_waitcnt vmcnt(1)
	v_pk_fma_f32 v[56:57], v[56:57], v[60:61], v[64:65]
	v_pk_fma_f32 v[54:55], v[54:55], v[58:59], v[62:63]
	s_waitcnt vmcnt(0)
	v_pk_fma_f32 v[52:53], v[52:53], v[68:69], v[72:73]
	v_pk_fma_f32 v[50:51], v[50:51], v[66:67], v[70:71]
	v_cvt_pk_bf16_f32 v54, v54, v55
	v_cvt_pk_bf16_f32 v55, v56, v57
	v_lshl_add_u64 v[56:57], v[82:83], 1, v[74:75]
	v_cvt_pk_bf16_f32 v50, v50, v51
	v_cvt_pk_bf16_f32 v51, v52, v53
	v_add_u32_e32 v0, 0xfffff020, v84
	global_store_dwordx2 v[56:57], v[50:51], off offset:32
	v_or_b32_e32 v66, 32, v84
	v_lshrrev_b32_e32 v50, 11, v0
	s_movk_i32 s0, 0x1000
	v_add_u32_e32 v50, 1, v50
	v_cmp_gt_i32_e32 vcc, s0, v66
	global_store_dwordx2 v[56:57], v[54:55], off
	v_ashrrev_i32_e32 v67, 31, v66
	v_cndmask_b32_e64 v52, v50, 0, vcc
	v_mov_b64_e32 v[50:51], s[6:7]
	v_mad_u64_u32 v[50:51], s[0:1], v52, s65, v[50:51]
	v_lshl_add_u64 v[58:59], v[82:83], 2, v[50:51]
	global_load_dwordx4 v[50:53], v[58:59], off
	v_cndmask_b32_e32 v54, v0, v66, vcc
	v_mov_b32_e32 v0, s64
	v_mov_b32_e32 v56, s96
	v_cndmask_b32_e32 v55, 0, v67, vcc
	v_cndmask_b32_e32 v57, v0, v56, vcc
	v_mov_b32_e32 v0, s62
	v_mov_b32_e32 v56, s66
	v_cndmask_b32_e32 v56, v0, v56, vcc
	v_lshlrev_b64 v[60:61], 12, v[54:55]
	v_lshl_add_u64 v[62:63], v[56:57], 0, v[60:61]
	s_mov_b64 s[0:1], -1
	s_and_b64 vcc, exec, s[4:5]
	v_lshl_add_u64 v[68:69], v[82:83], 1, v[62:63]
	s_cbranch_vccnz .LBB0_129
	global_load_dwordx2 v[56:57], v[68:69], off
	v_lshl_add_u64 v[60:61], v[62:63], 0, v[60:61]
	v_lshl_add_u64 v[70:71], v[82:83], 2, v[60:61]
	s_cbranch_execnz .LBB0_131
	s_branch .LBB0_130

.LBB0_131:
	s_nop 0
	global_load_dwordx4 v[58:61], v[58:59], off offset:64
	s_and_b64 vcc, exec, s[4:5]
	s_mov_b64 s[0:1], -1
	s_cbranch_vccnz .LBB0_133
	global_load_dwordx2 v[64:65], v[68:69], off offset:32
	s_cbranch_execz .LBB0_134
	s_branch .LBB0_135

.LBB0_135:
	s_and_b64 vcc, exec, s[4:5]
	s_cbranch_vccnz .Lresid_f32_2
	s_waitcnt vmcnt(0)
	v_lshlrev_b32_e32 v54, 16, v56
	v_and_b32_e32 v55, 0xffff0000, v56
	v_lshlrev_b32_e32 v56, 16, v57
	v_and_b32_e32 v57, 0xffff0000, v57
	v_lshlrev_b32_e32 v62, 16, v64
	v_and_b32_e32 v63, 0xffff0000, v64
	v_lshlrev_b32_e32 v64, 16, v65
	v_and_b32_e32 v65, 0xffff0000, v65
.Lresid_f32_2:
	v_lshlrev_b64 v[66:67], 12, v[66:67]
	v_pk_add_f32 v[48:49], v[48:49], 0 op_sel_hi:[1,0]
	v_pk_add_f32 v[46:47], v[46:47], 0 op_sel_hi:[1,0]
	v_pk_add_f32 v[44:45], v[44:45], 0 op_sel_hi:[1,0]
	v_pk_add_f32 v[42:43], v[42:43], 0 op_sel_hi:[1,0]
	v_lshl_add_u64 v[66:67], s[22:23], 0, v[66:67]
	s_waitcnt vmcnt(1)
	v_pk_fma_f32 v[48:49], v[48:49], v[52:53], v[56:57]
	v_pk_fma_f32 v[46:47], v[46:47], v[50:51], v[54:55]
	s_waitcnt vmcnt(0)
	v_pk_fma_f32 v[44:45], v[44:45], v[60:61], v[64:65]
	v_pk_fma_f32 v[42:43], v[42:43], v[58:59], v[62:63]
	v_cvt_pk_bf16_f32 v46, v46, v47
	v_cvt_pk_bf16_f32 v47, v48, v49
	v_lshl_add_u64 v[48:49], v[82:83], 1, v[66:67]
	v_cvt_pk_bf16_f32 v42, v42, v43
	v_cvt_pk_bf16_f32 v43, v44, v45
	v_add_u32_e32 v0, 0xfffff030, v84
	global_store_dwordx2 v[48:49], v[42:43], off offset:32
	v_or_b32_e32 v58, 48, v84
	v_lshrrev_b32_e32 v42, 11, v0
	s_movk_i32 s0, 0x1000
	v_add_u32_e32 v42, 1, v42
	v_cmp_gt_i32_e32 vcc, s0, v58
	global_store_dwordx2 v[48:49], v[46:47], off
	v_ashrrev_i32_e32 v59, 31, v58
	v_cndmask_b32_e64 v44, v42, 0, vcc
	v_mov_b64_e32 v[42:43], s[6:7]
	v_mad_u64_u32 v[42:43], s[0:1], v44, s65, v[42:43]
	v_lshl_add_u64 v[50:51], v[82:83], 2, v[42:43]
	global_load_dwordx4 v[42:45], v[50:51], off
	v_cndmask_b32_e32 v46, v0, v58, vcc
	v_mov_b32_e32 v0, s64
	v_mov_b32_e32 v48, s96
	v_cndmask_b32_e32 v47, 0, v59, vcc
	v_cndmask_b32_e32 v49, v0, v48, vcc
	v_mov_b32_e32 v0, s62
	v_mov_b32_e32 v48, s66
	v_cndmask_b32_e32 v48, v0, v48, vcc
	v_lshlrev_b64 v[52:53], 12, v[46:47]
	v_lshl_add_u64 v[54:55], v[48:49], 0, v[52:53]
	s_mov_b64 s[0:1], -1
	s_and_b64 vcc, exec, s[4:5]
	v_lshl_add_u64 v[60:61], v[82:83], 1, v[54:55]
	s_cbranch_vccnz .LBB0_137
	global_load_dwordx2 v[48:49], v[60:61], off
	v_lshl_add_u64 v[52:53], v[54:55], 0, v[52:53]
	v_lshl_add_u64 v[62:63], v[82:83], 2, v[52:53]
	s_cbranch_execnz .LBB0_139
	s_branch .LBB0_138

.LBB0_139:
	s_nop 0
	global_load_dwordx4 v[50:53], v[50:51], off offset:64
	s_and_b64 vcc, exec, s[4:5]
	s_mov_b64 s[0:1], -1
	s_cbranch_vccnz .LBB0_141
	global_load_dwordx2 v[56:57], v[60:61], off offset:32
	s_cbranch_execz .LBB0_142
	s_branch .LBB0_143

.LBB0_143:
	s_and_b64 vcc, exec, s[4:5]
	s_cbranch_vccnz .Lresid_f32_3
	s_waitcnt vmcnt(0)
	v_lshlrev_b32_e32 v46, 16, v48
	v_and_b32_e32 v47, 0xffff0000, v48
	v_lshlrev_b32_e32 v48, 16, v49
	v_and_b32_e32 v49, 0xffff0000, v49
	v_lshlrev_b32_e32 v54, 16, v56
	v_and_b32_e32 v55, 0xffff0000, v56
	v_lshlrev_b32_e32 v56, 16, v57
	v_and_b32_e32 v57, 0xffff0000, v57
.Lresid_f32_3:
	v_lshlrev_b64 v[58:59], 12, v[58:59]
	v_pk_add_f32 v[40:41], v[40:41], 0 op_sel_hi:[1,0]
	v_pk_add_f32 v[38:39], v[38:39], 0 op_sel_hi:[1,0]
	v_pk_add_f32 v[36:37], v[36:37], 0 op_sel_hi:[1,0]
	v_pk_add_f32 v[34:35], v[34:35], 0 op_sel_hi:[1,0]
	v_lshl_add_u64 v[58:59], s[22:23], 0, v[58:59]
	s_waitcnt vmcnt(1)
	v_pk_fma_f32 v[40:41], v[40:41], v[44:45], v[48:49]
	v_pk_fma_f32 v[38:39], v[38:39], v[42:43], v[46:47]
	s_waitcnt vmcnt(0)
	v_pk_fma_f32 v[36:37], v[36:37], v[52:53], v[56:57]
	v_pk_fma_f32 v[34:35], v[34:35], v[50:51], v[54:55]
	v_cvt_pk_bf16_f32 v38, v38, v39
	v_cvt_pk_bf16_f32 v39, v40, v41
	v_lshl_add_u64 v[40:41], v[82:83], 1, v[58:59]
	v_cvt_pk_bf16_f32 v34, v34, v35
	v_cvt_pk_bf16_f32 v35, v36, v37
	v_add_u32_e32 v0, 0xfffff080, v84
	global_store_dwordx2 v[40:41], v[34:35], off offset:32
	v_lshrrev_b32_e32 v34, 11, v0
	s_movk_i32 s0, 0xf80
	v_add_u32_e32 v34, 1, v34
	v_cmp_gt_i32_e32 vcc, s0, v84
	global_store_dwordx2 v[40:41], v[38:39], off
	v_add_u32_e32 v50, 0x80, v84
	v_cndmask_b32_e64 v36, v34, 0, vcc
	v_mov_b64_e32 v[34:35], s[6:7]
	v_mad_u64_u32 v[34:35], s[0:1], v36, s65, v[34:35]
	v_lshl_add_u64 v[42:43], v[82:83], 2, v[34:35]
	global_load_dwordx4 v[34:37], v[42:43], off
	v_ashrrev_i32_e32 v51, 31, v50
	v_cndmask_b32_e32 v38, v0, v50, vcc
	v_mov_b32_e32 v0, s64
	v_mov_b32_e32 v40, s96
	v_cndmask_b32_e32 v39, 0, v51, vcc
	v_cndmask_b32_e32 v41, v0, v40, vcc
	v_mov_b32_e32 v0, s62
	v_mov_b32_e32 v40, s66
	v_cndmask_b32_e32 v40, v0, v40, vcc
	v_lshlrev_b64 v[44:45], 12, v[38:39]
	v_lshl_add_u64 v[46:47], v[40:41], 0, v[44:45]
	s_mov_b64 s[0:1], -1
	s_and_b64 vcc, exec, s[4:5]
	v_lshl_add_u64 v[52:53], v[82:83], 1, v[46:47]
	s_cbranch_vccnz .LBB0_145
	global_load_dwordx2 v[40:41], v[52:53], off
	v_lshl_add_u64 v[44:45], v[46:47], 0, v[44:45]
	v_lshl_add_u64 v[54:55], v[82:83], 2, v[44:45]
	s_cbranch_execnz .LBB0_147
	s_branch .LBB0_146

.LBB0_147:
	s_nop 0
	global_load_dwordx4 v[42:45], v[42:43], off offset:64
	s_and_b64 vcc, exec, s[4:5]
	s_mov_b64 s[0:1], -1
	s_cbranch_vccnz .LBB0_149
	global_load_dwordx2 v[48:49], v[52:53], off offset:32
	s_cbranch_execz .LBB0_150
	s_branch .LBB0_151

.LBB0_151:
	s_and_b64 vcc, exec, s[4:5]
	s_cbranch_vccnz .Lresid_f32_4
	s_waitcnt vmcnt(0)
	v_lshlrev_b32_e32 v38, 16, v40
	v_and_b32_e32 v39, 0xffff0000, v40
	v_lshlrev_b32_e32 v40, 16, v41
	v_and_b32_e32 v41, 0xffff0000, v41
	v_lshlrev_b32_e32 v46, 16, v48
	v_and_b32_e32 v47, 0xffff0000, v48
	v_lshlrev_b32_e32 v48, 16, v49
	v_and_b32_e32 v49, 0xffff0000, v49
.Lresid_f32_4:
	v_lshlrev_b64 v[50:51], 12, v[50:51]
	v_pk_add_f32 v[32:33], v[32:33], 0 op_sel_hi:[1,0]
	v_pk_add_f32 v[30:31], v[30:31], 0 op_sel_hi:[1,0]
	v_pk_add_f32 v[28:29], v[28:29], 0 op_sel_hi:[1,0]
	v_pk_add_f32 v[26:27], v[26:27], 0 op_sel_hi:[1,0]
	v_lshl_add_u64 v[50:51], s[22:23], 0, v[50:51]
	s_waitcnt vmcnt(1)
	v_pk_fma_f32 v[32:33], v[32:33], v[36:37], v[40:41]
	v_pk_fma_f32 v[30:31], v[30:31], v[34:35], v[38:39]
	s_waitcnt vmcnt(0)
	v_pk_fma_f32 v[28:29], v[28:29], v[44:45], v[48:49]
	v_pk_fma_f32 v[26:27], v[26:27], v[42:43], v[46:47]
	v_cvt_pk_bf16_f32 v30, v30, v31
	v_cvt_pk_bf16_f32 v31, v32, v33
	v_lshl_add_u64 v[32:33], v[82:83], 1, v[50:51]
	v_cvt_pk_bf16_f32 v26, v26, v27
	v_cvt_pk_bf16_f32 v27, v28, v29
	v_add_u32_e32 v0, 0xfffff090, v84
	global_store_dwordx2 v[32:33], v[26:27], off offset:32
	v_lshrrev_b32_e32 v26, 11, v0
	s_movk_i32 s0, 0xf70
	v_add_u32_e32 v26, 1, v26
	v_cmp_gt_i32_e32 vcc, s0, v84
	global_store_dwordx2 v[32:33], v[30:31], off
	v_add_u32_e32 v42, 0x90, v84
	v_cndmask_b32_e64 v28, v26, 0, vcc
	v_mov_b64_e32 v[26:27], s[6:7]
	v_mad_u64_u32 v[26:27], s[0:1], v28, s65, v[26:27]
	v_lshl_add_u64 v[34:35], v[82:83], 2, v[26:27]
	global_load_dwordx4 v[26:29], v[34:35], off
	v_ashrrev_i32_e32 v43, 31, v42
	v_cndmask_b32_e32 v30, v0, v42, vcc
	v_mov_b32_e32 v0, s64
	v_mov_b32_e32 v32, s96
	v_cndmask_b32_e32 v31, 0, v43, vcc
	v_cndmask_b32_e32 v33, v0, v32, vcc
	v_mov_b32_e32 v0, s62
	v_mov_b32_e32 v32, s66
	v_cndmask_b32_e32 v32, v0, v32, vcc
	v_lshlrev_b64 v[36:37], 12, v[30:31]
	v_lshl_add_u64 v[38:39], v[32:33], 0, v[36:37]
	s_mov_b64 s[0:1], -1
	s_and_b64 vcc, exec, s[4:5]
	v_lshl_add_u64 v[44:45], v[82:83], 1, v[38:39]
	s_cbranch_vccnz .LBB0_153
	global_load_dwordx2 v[32:33], v[44:45], off
	v_lshl_add_u64 v[36:37], v[38:39], 0, v[36:37]
	v_lshl_add_u64 v[46:47], v[82:83], 2, v[36:37]
	s_cbranch_execnz .LBB0_155
	s_branch .LBB0_154

.LBB0_155:
	s_nop 0
	global_load_dwordx4 v[34:37], v[34:35], off offset:64
	s_and_b64 vcc, exec, s[4:5]
	s_mov_b64 s[0:1], -1
	s_cbranch_vccnz .LBB0_157
	global_load_dwordx2 v[40:41], v[44:45], off offset:32
	s_cbranch_execz .LBB0_158
	s_branch .LBB0_159

.LBB0_159:
	s_and_b64 vcc, exec, s[4:5]
	s_cbranch_vccnz .Lresid_f32_5
	s_waitcnt vmcnt(0)
	v_lshlrev_b32_e32 v30, 16, v32
	v_and_b32_e32 v31, 0xffff0000, v32
	v_lshlrev_b32_e32 v32, 16, v33
	v_and_b32_e32 v33, 0xffff0000, v33
	v_lshlrev_b32_e32 v38, 16, v40
	v_and_b32_e32 v39, 0xffff0000, v40
	v_lshlrev_b32_e32 v40, 16, v41
	v_and_b32_e32 v41, 0xffff0000, v41
.Lresid_f32_5:
	v_lshlrev_b64 v[42:43], 12, v[42:43]
	v_pk_add_f32 v[24:25], v[24:25], 0 op_sel_hi:[1,0]
	v_pk_add_f32 v[22:23], v[22:23], 0 op_sel_hi:[1,0]
	v_pk_add_f32 v[20:21], v[20:21], 0 op_sel_hi:[1,0]
	v_pk_add_f32 v[18:19], v[18:19], 0 op_sel_hi:[1,0]
	v_lshl_add_u64 v[42:43], s[22:23], 0, v[42:43]
	s_waitcnt vmcnt(1)
	v_pk_fma_f32 v[24:25], v[24:25], v[28:29], v[32:33]
	v_pk_fma_f32 v[22:23], v[22:23], v[26:27], v[30:31]
	s_waitcnt vmcnt(0)
	v_pk_fma_f32 v[20:21], v[20:21], v[36:37], v[40:41]
	v_pk_fma_f32 v[18:19], v[18:19], v[34:35], v[38:39]
	v_cvt_pk_bf16_f32 v22, v22, v23
	v_cvt_pk_bf16_f32 v23, v24, v25
	v_lshl_add_u64 v[24:25], v[82:83], 1, v[42:43]
	v_cvt_pk_bf16_f32 v18, v18, v19
	v_cvt_pk_bf16_f32 v19, v20, v21
	v_add_u32_e32 v0, 0xfffff0a0, v84
	global_store_dwordx2 v[24:25], v[18:19], off offset:32
	v_lshrrev_b32_e32 v18, 11, v0
	s_movk_i32 s0, 0xf60
	v_add_u32_e32 v18, 1, v18
	v_cmp_gt_i32_e32 vcc, s0, v84
	global_store_dwordx2 v[24:25], v[22:23], off
	v_add_u32_e32 v34, 0xa0, v84
	v_cndmask_b32_e64 v20, v18, 0, vcc
	v_mov_b64_e32 v[18:19], s[6:7]
	v_mad_u64_u32 v[18:19], s[0:1], v20, s65, v[18:19]
	v_lshl_add_u64 v[26:27], v[82:83], 2, v[18:19]
	global_load_dwordx4 v[18:21], v[26:27], off
	v_ashrrev_i32_e32 v35, 31, v34
	v_cndmask_b32_e32 v22, v0, v34, vcc
	v_mov_b32_e32 v0, s64
	v_mov_b32_e32 v24, s96
	v_cndmask_b32_e32 v23, 0, v35, vcc
	v_cndmask_b32_e32 v25, v0, v24, vcc
	v_mov_b32_e32 v0, s62
	v_mov_b32_e32 v24, s66
	v_cndmask_b32_e32 v24, v0, v24, vcc
	v_lshlrev_b64 v[28:29], 12, v[22:23]
	v_lshl_add_u64 v[30:31], v[24:25], 0, v[28:29]
	s_mov_b64 s[0:1], -1
	s_and_b64 vcc, exec, s[4:5]
	v_lshl_add_u64 v[36:37], v[82:83], 1, v[30:31]
	s_cbranch_vccnz .LBB0_161
	global_load_dwordx2 v[24:25], v[36:37], off
	v_lshl_add_u64 v[28:29], v[30:31], 0, v[28:29]
	v_lshl_add_u64 v[38:39], v[82:83], 2, v[28:29]
	s_cbranch_execnz .LBB0_163
	s_branch .LBB0_162

.LBB0_163:
	s_nop 0
	global_load_dwordx4 v[26:29], v[26:27], off offset:64
	s_and_b64 vcc, exec, s[4:5]
	s_mov_b64 s[0:1], -1
	s_cbranch_vccnz .LBB0_165
	global_load_dwordx2 v[32:33], v[36:37], off offset:32
	s_cbranch_execz .LBB0_166
	s_branch .LBB0_167

.LBB0_167:
	s_and_b64 vcc, exec, s[4:5]
	s_cbranch_vccnz .Lresid_f32_6
	s_waitcnt vmcnt(0)
	v_lshlrev_b32_e32 v22, 16, v24
	v_and_b32_e32 v23, 0xffff0000, v24
	v_lshlrev_b32_e32 v24, 16, v25
	v_and_b32_e32 v25, 0xffff0000, v25
	v_lshlrev_b32_e32 v30, 16, v32
	v_and_b32_e32 v31, 0xffff0000, v32
	v_lshlrev_b32_e32 v32, 16, v33
	v_and_b32_e32 v33, 0xffff0000, v33
.Lresid_f32_6:
	v_lshlrev_b64 v[34:35], 12, v[34:35]
	v_pk_add_f32 v[16:17], v[16:17], 0 op_sel_hi:[1,0]
	v_pk_add_f32 v[14:15], v[14:15], 0 op_sel_hi:[1,0]
	v_pk_add_f32 v[12:13], v[12:13], 0 op_sel_hi:[1,0]
	v_pk_add_f32 v[10:11], v[10:11], 0 op_sel_hi:[1,0]
	v_lshl_add_u64 v[34:35], s[22:23], 0, v[34:35]
	s_waitcnt vmcnt(1)
	v_pk_fma_f32 v[16:17], v[16:17], v[20:21], v[24:25]
	v_pk_fma_f32 v[14:15], v[14:15], v[18:19], v[22:23]
	s_waitcnt vmcnt(0)
	v_pk_fma_f32 v[12:13], v[12:13], v[28:29], v[32:33]
	v_pk_fma_f32 v[10:11], v[10:11], v[26:27], v[30:31]
	v_cvt_pk_bf16_f32 v14, v14, v15
	v_cvt_pk_bf16_f32 v15, v16, v17
	v_lshl_add_u64 v[16:17], v[82:83], 1, v[34:35]
	v_cvt_pk_bf16_f32 v10, v10, v11
	v_cvt_pk_bf16_f32 v11, v12, v13
	v_add_u32_e32 v0, 0xfffff0b0, v84
	global_store_dwordx2 v[16:17], v[10:11], off offset:32
	v_lshrrev_b32_e32 v10, 11, v0
	s_movk_i32 s0, 0xf50
	v_add_u32_e32 v10, 1, v10
	v_cmp_gt_i32_e32 vcc, s0, v84
	global_store_dwordx2 v[16:17], v[14:15], off
	v_add_u32_e32 v26, 0xb0, v84
	v_cndmask_b32_e64 v12, v10, 0, vcc
	v_mov_b64_e32 v[10:11], s[6:7]
	v_mad_u64_u32 v[10:11], s[0:1], v12, s65, v[10:11]
	v_lshl_add_u64 v[18:19], v[82:83], 2, v[10:11]
	global_load_dwordx4 v[10:13], v[18:19], off
	v_ashrrev_i32_e32 v27, 31, v26
	v_cndmask_b32_e32 v14, v0, v26, vcc
	v_mov_b32_e32 v0, s64
	v_mov_b32_e32 v16, s96
	v_cndmask_b32_e32 v15, 0, v27, vcc
	v_cndmask_b32_e32 v17, v0, v16, vcc
	v_mov_b32_e32 v0, s62
	v_mov_b32_e32 v16, s66
	v_cndmask_b32_e32 v16, v0, v16, vcc
	v_lshlrev_b64 v[20:21], 12, v[14:15]
	v_lshl_add_u64 v[22:23], v[16:17], 0, v[20:21]
	s_mov_b64 s[0:1], -1
	s_and_b64 vcc, exec, s[4:5]
	v_lshl_add_u64 v[28:29], v[82:83], 1, v[22:23]
	s_cbranch_vccnz .LBB0_169
	global_load_dwordx2 v[16:17], v[28:29], off
	v_lshl_add_u64 v[20:21], v[22:23], 0, v[20:21]
	v_lshl_add_u64 v[30:31], v[82:83], 2, v[20:21]
	s_cbranch_execnz .LBB0_171
	s_branch .LBB0_170

.LBB0_171:
	s_nop 0
	global_load_dwordx4 v[18:21], v[18:19], off offset:64
	s_and_b64 vcc, exec, s[4:5]
	s_mov_b64 s[0:1], -1
	s_cbranch_vccnz .LBB0_173
	global_load_dwordx2 v[24:25], v[28:29], off offset:32
	s_cbranch_execnz .LBB0_104
	s_branch .LBB0_174

.LBB0_176:
	s_and_b64 vcc, exec, s[4:5]
	s_cbranch_vccnz .Lresid_f32_15
	s_waitcnt vmcnt(0)
	v_lshlrev_b32_e32 v22, 16, v24
	v_and_b32_e32 v23, 0xffff0000, v24
	v_lshlrev_b32_e32 v24, 16, v25
	v_and_b32_e32 v25, 0xffff0000, v25
	v_lshlrev_b32_e32 v30, 16, v32
	v_and_b32_e32 v31, 0xffff0000, v32
	v_lshlrev_b32_e32 v32, 16, v33
	v_and_b32_e32 v33, 0xffff0000, v33
	v_lshlrev_b32_e32 v38, 16, v40
	v_and_b32_e32 v39, 0xffff0000, v40
	v_lshlrev_b32_e32 v40, 16, v41
	v_and_b32_e32 v41, 0xffff0000, v41
	v_lshlrev_b32_e32 v46, 16, v48
	v_and_b32_e32 v47, 0xffff0000, v48
	v_lshlrev_b32_e32 v48, 16, v49
	v_and_b32_e32 v49, 0xffff0000, v49

.LBB0_183:
	s_or_b64 exec, exec, s[0:1]
	v_or_b32_e32 v0, s10, v146
	v_lshl_add_u32 v164, v143, 6, v0
	v_lshlrev_b32_e32 v0, 5, v144
	v_lshlrev_b32_e32 v130, 2, v145
	v_or3_b32 v162, v0, v130, s8
	v_add_u32_e32 v0, 0xfffff000, v164
	v_lshrrev_b32_e32 v130, 11, v0
	s_movk_i32 s0, 0x1000
	v_add_u32_e32 v130, 1, v130
	v_cmp_gt_i32_e32 vcc, s0, v164
	v_ashrrev_i32_e32 v163, 31, v162
	v_ashrrev_i32_e32 v165, 31, v164
	v_cndmask_b32_e64 v132, v130, 0, vcc
	v_mov_b64_e32 v[130:131], s[6:7]
	v_mad_u64_u32 v[130:131], s[0:1], v132, s65, v[130:131]
	v_lshl_add_u64 v[154:155], v[162:163], 2, v[130:131]
	global_load_dwordx4 v[130:133], v[154:155], off
	v_cndmask_b32_e32 v134, v0, v164, vcc
	v_mov_b32_e32 v0, s64
	v_mov_b32_e32 v136, s96
	v_cndmask_b32_e32 v135, 0, v165, vcc
	v_cndmask_b32_e32 v137, v0, v136, vcc
	v_mov_b32_e32 v0, s62
	v_mov_b32_e32 v136, s66
	v_cndmask_b32_e32 v136, v0, v136, vcc
	v_lshlrev_b64 v[138:139], 12, v[134:135]
	v_lshl_add_u64 v[140:141], v[136:137], 0, v[138:139]
	s_mov_b64 s[0:1], -1
	s_and_b64 vcc, exec, s[4:5]
	v_lshl_add_u64 v[166:167], v[162:163], 1, v[140:141]
	s_cbranch_vccnz .LBB0_185
	global_load_dwordx2 v[136:137], v[166:167], off
	v_lshl_add_u64 v[138:139], v[140:141], 0, v[138:139]
	v_lshl_add_u64 v[168:169], v[162:163], 2, v[138:139]
	s_cbranch_execnz .LBB0_187
	s_branch .LBB0_186

.LBB0_187:
	global_load_dwordx4 v[138:141], v[154:155], off offset:64
	s_and_b64 vcc, exec, s[4:5]
	s_mov_b64 s[0:1], -1
	s_cbranch_vccnz .LBB0_189
	global_load_dwordx2 v[144:145], v[166:167], off offset:32
	s_cbranch_execnz .LBB0_191
	s_branch .LBB0_190

.LBB0_191:
	global_load_dwordx4 v[146:149], v[154:155], off offset:512
	s_and_b64 vcc, exec, s[4:5]
	s_mov_b64 s[0:1], -1
	s_cbranch_vccnz .LBB0_193
	global_load_dwordx2 v[152:153], v[166:167], off offset:256
	s_cbranch_execnz .LBB0_195
	s_branch .LBB0_194

.LBB0_195:
	s_nop 0
	global_load_dwordx4 v[154:157], v[154:155], off offset:576
	s_and_b64 vcc, exec, s[4:5]
	s_mov_b64 s[0:1], -1
	s_cbranch_vccnz .LBB0_197
	global_load_dwordx2 v[160:161], v[166:167], off offset:288
	s_cbranch_execz .LBB0_198
	s_branch .LBB0_199

.LBB0_199:
	s_and_b64 vcc, exec, s[4:5]
	s_cbranch_vccnz .Lresid_f32_8
	s_waitcnt vmcnt(0)
	v_lshlrev_b32_e32 v134, 16, v136
	v_and_b32_e32 v135, 0xffff0000, v136
	v_lshlrev_b32_e32 v136, 16, v137
	v_and_b32_e32 v137, 0xffff0000, v137
	v_lshlrev_b32_e32 v142, 16, v144
	v_and_b32_e32 v143, 0xffff0000, v144
	v_lshlrev_b32_e32 v144, 16, v145
	v_and_b32_e32 v145, 0xffff0000, v145
	v_lshlrev_b32_e32 v150, 16, v152
	v_and_b32_e32 v151, 0xffff0000, v152
	v_lshlrev_b32_e32 v152, 16, v153
	v_and_b32_e32 v153, 0xffff0000, v153
	v_lshlrev_b32_e32 v158, 16, v160
	v_and_b32_e32 v159, 0xffff0000, v160
	v_lshlrev_b32_e32 v160, 16, v161
	v_and_b32_e32 v161, 0xffff0000, v161
.Lresid_f32_8:
	v_lshlrev_b64 v[166:167], 12, v[164:165]
	v_pk_add_f32 v[128:129], v[128:129], 0 op_sel_hi:[1,0]
	v_pk_add_f32 v[126:127], v[126:127], 0 op_sel_hi:[1,0]
	v_pk_add_f32 v[120:121], v[120:121], 0 op_sel_hi:[1,0]
	v_pk_add_f32 v[118:119], v[118:119], 0 op_sel_hi:[1,0]
	v_pk_add_f32 v[116:117], v[116:117], 0 op_sel_hi:[1,0]
	v_pk_add_f32 v[114:115], v[114:115], 0 op_sel_hi:[1,0]
	v_lshl_add_u64 v[166:167], s[22:23], 0, v[166:167]
	s_waitcnt vmcnt(3)
	v_pk_fma_f32 v[128:129], v[128:129], v[132:133], v[136:137]
	v_pk_fma_f32 v[126:127], v[126:127], v[130:131], v[134:135]
	s_waitcnt vmcnt(2)
	v_pk_fma_f32 v[120:121], v[120:121], v[140:141], v[144:145]
	v_pk_fma_f32 v[118:119], v[118:119], v[138:139], v[142:143]
	s_waitcnt vmcnt(0)
	v_pk_fma_f32 v[116:117], v[116:117], v[156:157], v[160:161]
	v_pk_fma_f32 v[114:115], v[114:115], v[154:155], v[158:159]
	v_cvt_pk_bf16_f32 v126, v126, v127
	v_cvt_pk_bf16_f32 v127, v128, v129
	v_lshl_add_u64 v[128:129], v[162:163], 1, v[166:167]
	v_cvt_pk_bf16_f32 v118, v118, v119
	v_cvt_pk_bf16_f32 v119, v120, v121
	v_pk_add_f32 v[120:121], v[122:123], 0 op_sel_hi:[1,0]
	v_cvt_pk_bf16_f32 v114, v114, v115
	v_cvt_pk_bf16_f32 v115, v116, v117
	v_add_u32_e32 v0, 0xfffff010, v164
	v_pk_fma_f32 v[120:121], v[120:121], v[146:147], v[150:151]
	global_store_dwordx2 v[128:129], v[114:115], off offset:288
	v_or_b32_e32 v146, 16, v164
	v_lshrrev_b32_e32 v114, 11, v0
	s_movk_i32 s0, 0x1000
	global_store_dwordx2 v[128:129], v[118:119], off offset:32
	v_pk_add_f32 v[118:119], v[124:125], 0 op_sel_hi:[1,0]
	v_add_u32_e32 v114, 1, v114
	v_cmp_gt_i32_e32 vcc, s0, v146
	v_pk_fma_f32 v[118:119], v[118:119], v[148:149], v[152:153]
	v_cvt_pk_bf16_f32 v120, v120, v121
	v_cndmask_b32_e64 v116, v114, 0, vcc
	v_mov_b64_e32 v[114:115], s[6:7]
	v_cvt_pk_bf16_f32 v121, v118, v119
	v_mad_u64_u32 v[114:115], s[0:1], v116, s65, v[114:115]
	global_store_dwordx2 v[128:129], v[126:127], off
	global_store_dwordx2 v[128:129], v[120:121], off offset:256
	v_lshl_add_u64 v[138:139], v[162:163], 2, v[114:115]
	global_load_dwordx4 v[114:117], v[138:139], off
	v_ashrrev_i32_e32 v147, 31, v146
	v_cndmask_b32_e32 v118, v0, v146, vcc
	v_mov_b32_e32 v0, s64
	v_mov_b32_e32 v120, s96
	v_cndmask_b32_e32 v119, 0, v147, vcc
	v_cndmask_b32_e32 v121, v0, v120, vcc
	v_mov_b32_e32 v0, s62
	v_mov_b32_e32 v120, s66
	v_cndmask_b32_e32 v120, v0, v120, vcc
	v_lshlrev_b64 v[122:123], 12, v[118:119]
	v_lshl_add_u64 v[124:125], v[120:121], 0, v[122:123]
	s_mov_b64 s[0:1], -1
	s_and_b64 vcc, exec, s[4:5]
	v_lshl_add_u64 v[148:149], v[162:163], 1, v[124:125]
	s_cbranch_vccnz .LBB0_201
	global_load_dwordx2 v[120:121], v[148:149], off
	v_lshl_add_u64 v[122:123], v[124:125], 0, v[122:123]
	v_lshl_add_u64 v[150:151], v[162:163], 2, v[122:123]
	s_cbranch_execnz .LBB0_203
	s_branch .LBB0_202

.LBB0_203:
	global_load_dwordx4 v[122:125], v[138:139], off offset:64
	s_and_b64 vcc, exec, s[4:5]
	s_mov_b64 s[0:1], -1
	s_cbranch_vccnz .LBB0_205
	global_load_dwordx2 v[128:129], v[148:149], off offset:32
	s_cbranch_execnz .LBB0_207
	s_branch .LBB0_206

.LBB0_207:
	global_load_dwordx4 v[130:133], v[138:139], off offset:512
	s_and_b64 vcc, exec, s[4:5]
	s_mov_b64 s[0:1], -1
	s_cbranch_vccnz .LBB0_209
	global_load_dwordx2 v[136:137], v[148:149], off offset:256
	s_cbranch_execnz .LBB0_211
	s_branch .LBB0_210

.LBB0_211:
	s_nop 0
	global_load_dwordx4 v[138:141], v[138:139], off offset:576
	s_and_b64 vcc, exec, s[4:5]
	s_mov_b64 s[0:1], -1
	s_cbranch_vccnz .LBB0_213
	global_load_dwordx2 v[144:145], v[148:149], off offset:288
	s_cbranch_execz .LBB0_214
	s_branch .LBB0_215

.LBB0_215:
	s_and_b64 vcc, exec, s[4:5]
	s_cbranch_vccnz .Lresid_f32_9
	s_waitcnt vmcnt(0)
	v_lshlrev_b32_e32 v118, 16, v120
	v_and_b32_e32 v119, 0xffff0000, v120
	v_lshlrev_b32_e32 v120, 16, v121
	v_and_b32_e32 v121, 0xffff0000, v121
	v_lshlrev_b32_e32 v126, 16, v128
	v_and_b32_e32 v127, 0xffff0000, v128
	v_lshlrev_b32_e32 v128, 16, v129
	v_and_b32_e32 v129, 0xffff0000, v129
	v_lshlrev_b32_e32 v134, 16, v136
	v_and_b32_e32 v135, 0xffff0000, v136
	v_lshlrev_b32_e32 v136, 16, v137
	v_and_b32_e32 v137, 0xffff0000, v137
	v_lshlrev_b32_e32 v142, 16, v144
	v_and_b32_e32 v143, 0xffff0000, v144
	v_lshlrev_b32_e32 v144, 16, v145
	v_and_b32_e32 v145, 0xffff0000, v145
.Lresid_f32_9:
	v_lshlrev_b64 v[146:147], 12, v[146:147]
	v_pk_add_f32 v[112:113], v[112:113], 0 op_sel_hi:[1,0]
	v_pk_add_f32 v[110:111], v[110:111], 0 op_sel_hi:[1,0]
	v_pk_add_f32 v[104:105], v[104:105], 0 op_sel_hi:[1,0]
	v_pk_add_f32 v[102:103], v[102:103], 0 op_sel_hi:[1,0]
	v_pk_add_f32 v[100:101], v[100:101], 0 op_sel_hi:[1,0]
	v_pk_add_f32 v[98:99], v[98:99], 0 op_sel_hi:[1,0]
	v_lshl_add_u64 v[146:147], s[22:23], 0, v[146:147]
	s_waitcnt vmcnt(3)
	v_pk_fma_f32 v[112:113], v[112:113], v[116:117], v[120:121]
	v_pk_fma_f32 v[110:111], v[110:111], v[114:115], v[118:119]
	s_waitcnt vmcnt(2)
	v_pk_fma_f32 v[104:105], v[104:105], v[124:125], v[128:129]
	v_pk_fma_f32 v[102:103], v[102:103], v[122:123], v[126:127]
	s_waitcnt vmcnt(0)
	v_pk_fma_f32 v[100:101], v[100:101], v[140:141], v[144:145]
	v_pk_fma_f32 v[98:99], v[98:99], v[138:139], v[142:143]
	v_cvt_pk_bf16_f32 v110, v110, v111
	v_cvt_pk_bf16_f32 v111, v112, v113
	v_lshl_add_u64 v[112:113], v[162:163], 1, v[146:147]
	v_cvt_pk_bf16_f32 v102, v102, v103
	v_cvt_pk_bf16_f32 v103, v104, v105
	v_pk_add_f32 v[104:105], v[106:107], 0 op_sel_hi:[1,0]
	v_cvt_pk_bf16_f32 v98, v98, v99
	v_cvt_pk_bf16_f32 v99, v100, v101
	v_add_u32_e32 v0, 0xfffff020, v164
	v_pk_fma_f32 v[104:105], v[104:105], v[130:131], v[134:135]
	global_store_dwordx2 v[112:113], v[98:99], off offset:288
	v_or_b32_e32 v130, 32, v164
	v_lshrrev_b32_e32 v98, 11, v0
	s_movk_i32 s0, 0x1000
	global_store_dwordx2 v[112:113], v[102:103], off offset:32
	v_pk_add_f32 v[102:103], v[108:109], 0 op_sel_hi:[1,0]
	v_add_u32_e32 v98, 1, v98
	v_cmp_gt_i32_e32 vcc, s0, v130
	v_pk_fma_f32 v[102:103], v[102:103], v[132:133], v[136:137]
	v_cvt_pk_bf16_f32 v104, v104, v105
	v_cndmask_b32_e64 v100, v98, 0, vcc
	v_mov_b64_e32 v[98:99], s[6:7]
	v_cvt_pk_bf16_f32 v105, v102, v103
	v_mad_u64_u32 v[98:99], s[0:1], v100, s65, v[98:99]
	global_store_dwordx2 v[112:113], v[110:111], off
	global_store_dwordx2 v[112:113], v[104:105], off offset:256
	v_lshl_add_u64 v[122:123], v[162:163], 2, v[98:99]
	global_load_dwordx4 v[98:101], v[122:123], off
	v_ashrrev_i32_e32 v131, 31, v130
	v_cndmask_b32_e32 v102, v0, v130, vcc
	v_mov_b32_e32 v0, s64
	v_mov_b32_e32 v104, s96
	v_cndmask_b32_e32 v103, 0, v131, vcc
	v_cndmask_b32_e32 v105, v0, v104, vcc
	v_mov_b32_e32 v0, s62
	v_mov_b32_e32 v104, s66
	v_cndmask_b32_e32 v104, v0, v104, vcc
	v_lshlrev_b64 v[106:107], 12, v[102:103]
	v_lshl_add_u64 v[108:109], v[104:105], 0, v[106:107]
	s_mov_b64 s[0:1], -1
	s_and_b64 vcc, exec, s[4:5]
	v_lshl_add_u64 v[132:133], v[162:163], 1, v[108:109]
	s_cbranch_vccnz .LBB0_217
	global_load_dwordx2 v[104:105], v[132:133], off
	v_lshl_add_u64 v[106:107], v[108:109], 0, v[106:107]
	v_lshl_add_u64 v[134:135], v[162:163], 2, v[106:107]
	s_cbranch_execnz .LBB0_219
	s_branch .LBB0_218

.LBB0_219:
	global_load_dwordx4 v[106:109], v[122:123], off offset:64
	s_and_b64 vcc, exec, s[4:5]
	s_mov_b64 s[0:1], -1
	s_cbranch_vccnz .LBB0_221
	global_load_dwordx2 v[112:113], v[132:133], off offset:32
	s_cbranch_execnz .LBB0_223
	s_branch .LBB0_222

.LBB0_223:
	global_load_dwordx4 v[114:117], v[122:123], off offset:512
	s_and_b64 vcc, exec, s[4:5]
	s_mov_b64 s[0:1], -1
	s_cbranch_vccnz .LBB0_225
	global_load_dwordx2 v[120:121], v[132:133], off offset:256
	s_cbranch_execnz .LBB0_227
	s_branch .LBB0_226

.LBB0_227:
	s_nop 0
	global_load_dwordx4 v[122:125], v[122:123], off offset:576
	s_and_b64 vcc, exec, s[4:5]
	s_mov_b64 s[0:1], -1
	s_cbranch_vccnz .LBB0_229
	global_load_dwordx2 v[128:129], v[132:133], off offset:288
	s_cbranch_execz .LBB0_230
	s_branch .LBB0_231

.LBB0_231:
	s_and_b64 vcc, exec, s[4:5]
	s_cbranch_vccnz .Lresid_f32_10
	s_waitcnt vmcnt(0)
	v_lshlrev_b32_e32 v102, 16, v104
	v_and_b32_e32 v103, 0xffff0000, v104
	v_lshlrev_b32_e32 v104, 16, v105
	v_and_b32_e32 v105, 0xffff0000, v105
	v_lshlrev_b32_e32 v110, 16, v112
	v_and_b32_e32 v111, 0xffff0000, v112
	v_lshlrev_b32_e32 v112, 16, v113
	v_and_b32_e32 v113, 0xffff0000, v113
	v_lshlrev_b32_e32 v118, 16, v120
	v_and_b32_e32 v119, 0xffff0000, v120
	v_lshlrev_b32_e32 v120, 16, v121
	v_and_b32_e32 v121, 0xffff0000, v121
	v_lshlrev_b32_e32 v126, 16, v128
	v_and_b32_e32 v127, 0xffff0000, v128
	v_lshlrev_b32_e32 v128, 16, v129
	v_and_b32_e32 v129, 0xffff0000, v129
.Lresid_f32_10:
	v_lshlrev_b64 v[130:131], 12, v[130:131]
	v_pk_add_f32 v[96:97], v[96:97], 0 op_sel_hi:[1,0]
	v_pk_add_f32 v[94:95], v[94:95], 0 op_sel_hi:[1,0]
	v_pk_add_f32 v[88:89], v[88:89], 0 op_sel_hi:[1,0]
	v_pk_add_f32 v[86:87], v[86:87], 0 op_sel_hi:[1,0]
	v_pk_add_f32 v[84:85], v[84:85], 0 op_sel_hi:[1,0]
	v_pk_add_f32 v[82:83], v[82:83], 0 op_sel_hi:[1,0]
	v_lshl_add_u64 v[130:131], s[22:23], 0, v[130:131]
	s_waitcnt vmcnt(3)
	v_pk_fma_f32 v[96:97], v[96:97], v[100:101], v[104:105]
	v_pk_fma_f32 v[94:95], v[94:95], v[98:99], v[102:103]
	s_waitcnt vmcnt(2)
	v_pk_fma_f32 v[88:89], v[88:89], v[108:109], v[112:113]
	v_pk_fma_f32 v[86:87], v[86:87], v[106:107], v[110:111]
	s_waitcnt vmcnt(0)
	v_pk_fma_f32 v[84:85], v[84:85], v[124:125], v[128:129]
	v_pk_fma_f32 v[82:83], v[82:83], v[122:123], v[126:127]
	v_cvt_pk_bf16_f32 v94, v94, v95
	v_cvt_pk_bf16_f32 v95, v96, v97
	v_lshl_add_u64 v[96:97], v[162:163], 1, v[130:131]
	v_cvt_pk_bf16_f32 v86, v86, v87
	v_cvt_pk_bf16_f32 v87, v88, v89
	v_pk_add_f32 v[88:89], v[90:91], 0 op_sel_hi:[1,0]
	v_cvt_pk_bf16_f32 v82, v82, v83
	v_cvt_pk_bf16_f32 v83, v84, v85
	v_add_u32_e32 v0, 0xfffff030, v164
	v_pk_fma_f32 v[88:89], v[88:89], v[114:115], v[118:119]
	global_store_dwordx2 v[96:97], v[82:83], off offset:288
	v_or_b32_e32 v114, 48, v164
	v_lshrrev_b32_e32 v82, 11, v0
	s_movk_i32 s0, 0x1000
	global_store_dwordx2 v[96:97], v[86:87], off offset:32
	v_pk_add_f32 v[86:87], v[92:93], 0 op_sel_hi:[1,0]
	v_add_u32_e32 v82, 1, v82
	v_cmp_gt_i32_e32 vcc, s0, v114
	v_pk_fma_f32 v[86:87], v[86:87], v[116:117], v[120:121]
	v_cvt_pk_bf16_f32 v88, v88, v89
	v_cndmask_b32_e64 v84, v82, 0, vcc
	v_mov_b64_e32 v[82:83], s[6:7]
	v_cvt_pk_bf16_f32 v89, v86, v87
	v_mad_u64_u32 v[82:83], s[0:1], v84, s65, v[82:83]
	global_store_dwordx2 v[96:97], v[94:95], off
	global_store_dwordx2 v[96:97], v[88:89], off offset:256
	v_lshl_add_u64 v[106:107], v[162:163], 2, v[82:83]
	global_load_dwordx4 v[82:85], v[106:107], off
	v_ashrrev_i32_e32 v115, 31, v114
	v_cndmask_b32_e32 v86, v0, v114, vcc
	v_mov_b32_e32 v0, s64
	v_mov_b32_e32 v88, s96
	v_cndmask_b32_e32 v87, 0, v115, vcc
	v_cndmask_b32_e32 v89, v0, v88, vcc
	v_mov_b32_e32 v0, s62
	v_mov_b32_e32 v88, s66
	v_cndmask_b32_e32 v88, v0, v88, vcc
	v_lshlrev_b64 v[90:91], 12, v[86:87]
	v_lshl_add_u64 v[92:93], v[88:89], 0, v[90:91]
	s_mov_b64 s[0:1], -1
	s_and_b64 vcc, exec, s[4:5]
	v_lshl_add_u64 v[116:117], v[162:163], 1, v[92:93]
	s_cbranch_vccnz .LBB0_233
	global_load_dwordx2 v[88:89], v[116:117], off
	v_lshl_add_u64 v[90:91], v[92:93], 0, v[90:91]
	v_lshl_add_u64 v[118:119], v[162:163], 2, v[90:91]
	s_cbranch_execnz .LBB0_235
	s_branch .LBB0_234

.LBB0_235:
	global_load_dwordx4 v[90:93], v[106:107], off offset:64
	s_and_b64 vcc, exec, s[4:5]
	s_mov_b64 s[0:1], -1
	s_cbranch_vccnz .LBB0_237
	global_load_dwordx2 v[96:97], v[116:117], off offset:32
	s_cbranch_execnz .LBB0_239
	s_branch .LBB0_238

.LBB0_239:
	global_load_dwordx4 v[98:101], v[106:107], off offset:512
	s_and_b64 vcc, exec, s[4:5]
	s_mov_b64 s[0:1], -1
	s_cbranch_vccnz .LBB0_241
	global_load_dwordx2 v[104:105], v[116:117], off offset:256
	s_cbranch_execnz .LBB0_243
	s_branch .LBB0_242

.LBB0_243:
	s_nop 0
	global_load_dwordx4 v[106:109], v[106:107], off offset:576
	s_and_b64 vcc, exec, s[4:5]
	s_mov_b64 s[0:1], -1
	s_cbranch_vccnz .LBB0_245
	global_load_dwordx2 v[112:113], v[116:117], off offset:288
	s_cbranch_execz .LBB0_246
	s_branch .LBB0_247

.LBB0_247:
	s_and_b64 vcc, exec, s[4:5]
	s_cbranch_vccnz .Lresid_f32_11
	s_waitcnt vmcnt(0)
	v_lshlrev_b32_e32 v86, 16, v88
	v_and_b32_e32 v87, 0xffff0000, v88
	v_lshlrev_b32_e32 v88, 16, v89
	v_and_b32_e32 v89, 0xffff0000, v89
	v_lshlrev_b32_e32 v94, 16, v96
	v_and_b32_e32 v95, 0xffff0000, v96
	v_lshlrev_b32_e32 v96, 16, v97
	v_and_b32_e32 v97, 0xffff0000, v97
	v_lshlrev_b32_e32 v102, 16, v104
	v_and_b32_e32 v103, 0xffff0000, v104
	v_lshlrev_b32_e32 v104, 16, v105
	v_and_b32_e32 v105, 0xffff0000, v105
	v_lshlrev_b32_e32 v110, 16, v112
	v_and_b32_e32 v111, 0xffff0000, v112
	v_lshlrev_b32_e32 v112, 16, v113
	v_and_b32_e32 v113, 0xffff0000, v113
.Lresid_f32_11:
	v_lshlrev_b64 v[114:115], 12, v[114:115]
	v_pk_add_f32 v[80:81], v[80:81], 0 op_sel_hi:[1,0]
	v_pk_add_f32 v[78:79], v[78:79], 0 op_sel_hi:[1,0]
	v_pk_add_f32 v[68:69], v[68:69], 0 op_sel_hi:[1,0]
	v_pk_add_f32 v[66:67], v[66:67], 0 op_sel_hi:[1,0]
	v_lshl_add_u64 v[114:115], s[22:23], 0, v[114:115]
	s_waitcnt vmcnt(3)
	v_pk_fma_f32 v[80:81], v[80:81], v[84:85], v[88:89]
	v_pk_fma_f32 v[78:79], v[78:79], v[82:83], v[86:87]
	v_pk_add_f32 v[72:73], v[72:73], 0 op_sel_hi:[1,0]
	v_pk_add_f32 v[70:71], v[70:71], 0 op_sel_hi:[1,0]
	s_waitcnt vmcnt(0)
	v_pk_fma_f32 v[68:69], v[68:69], v[108:109], v[112:113]
	v_pk_fma_f32 v[66:67], v[66:67], v[106:107], v[110:111]
	v_cvt_pk_bf16_f32 v78, v78, v79
	v_cvt_pk_bf16_f32 v79, v80, v81
	v_lshl_add_u64 v[80:81], v[162:163], 1, v[114:115]
	v_pk_fma_f32 v[72:73], v[72:73], v[92:93], v[96:97]
	v_pk_fma_f32 v[70:71], v[70:71], v[90:91], v[94:95]
	v_cvt_pk_bf16_f32 v66, v66, v67
	v_cvt_pk_bf16_f32 v67, v68, v69
	v_add_u32_e32 v0, 0xfffff080, v164
	v_cvt_pk_bf16_f32 v70, v70, v71
	v_cvt_pk_bf16_f32 v71, v72, v73
	global_store_dwordx2 v[80:81], v[66:67], off offset:288
	v_lshrrev_b32_e32 v66, 11, v0
	s_movk_i32 s0, 0xf80
	global_store_dwordx2 v[80:81], v[70:71], off offset:32
	v_pk_add_f32 v[70:71], v[76:77], 0 op_sel_hi:[1,0]
	v_pk_add_f32 v[72:73], v[74:75], 0 op_sel_hi:[1,0]
	v_add_u32_e32 v66, 1, v66
	v_cmp_gt_i32_e32 vcc, s0, v164
	v_pk_fma_f32 v[70:71], v[70:71], v[100:101], v[104:105]
	v_pk_fma_f32 v[72:73], v[72:73], v[98:99], v[102:103]
	v_cndmask_b32_e64 v68, v66, 0, vcc
	v_mov_b64_e32 v[66:67], s[6:7]
	v_cvt_pk_bf16_f32 v72, v72, v73
	v_cvt_pk_bf16_f32 v73, v70, v71
	v_mad_u64_u32 v[66:67], s[0:1], v68, s65, v[66:67]
	global_store_dwordx2 v[80:81], v[78:79], off
	global_store_dwordx2 v[80:81], v[72:73], off offset:256
	v_lshl_add_u64 v[90:91], v[162:163], 2, v[66:67]
	global_load_dwordx4 v[66:69], v[90:91], off
	v_add_u32_e32 v98, 0x80, v164
	v_ashrrev_i32_e32 v99, 31, v98
	v_cndmask_b32_e32 v70, v0, v98, vcc
	v_mov_b32_e32 v0, s64
	v_mov_b32_e32 v72, s96
	v_cndmask_b32_e32 v71, 0, v99, vcc
	v_cndmask_b32_e32 v73, v0, v72, vcc
	v_mov_b32_e32 v0, s62
	v_mov_b32_e32 v72, s66
	v_cndmask_b32_e32 v72, v0, v72, vcc
	v_lshlrev_b64 v[74:75], 12, v[70:71]
	v_lshl_add_u64 v[76:77], v[72:73], 0, v[74:75]
	s_mov_b64 s[0:1], -1
	s_and_b64 vcc, exec, s[4:5]
	v_lshl_add_u64 v[100:101], v[162:163], 1, v[76:77]
	s_cbranch_vccnz .LBB0_249
	global_load_dwordx2 v[72:73], v[100:101], off
	v_lshl_add_u64 v[74:75], v[76:77], 0, v[74:75]
	v_lshl_add_u64 v[102:103], v[162:163], 2, v[74:75]
	s_cbranch_execnz .LBB0_251
	s_branch .LBB0_250

.LBB0_251:
	global_load_dwordx4 v[74:77], v[90:91], off offset:64
	s_and_b64 vcc, exec, s[4:5]
	s_mov_b64 s[0:1], -1
	s_cbranch_vccnz .LBB0_253
	global_load_dwordx2 v[80:81], v[100:101], off offset:32
	s_cbranch_execnz .LBB0_255
	s_branch .LBB0_254

.LBB0_255:
	global_load_dwordx4 v[82:85], v[90:91], off offset:512
	s_and_b64 vcc, exec, s[4:5]
	s_mov_b64 s[0:1], -1
	s_cbranch_vccnz .LBB0_257
	global_load_dwordx2 v[88:89], v[100:101], off offset:256
	s_cbranch_execnz .LBB0_259
	s_branch .LBB0_258

.LBB0_259:
	s_nop 0
	global_load_dwordx4 v[90:93], v[90:91], off offset:576
	s_and_b64 vcc, exec, s[4:5]
	s_mov_b64 s[0:1], -1
	s_cbranch_vccnz .LBB0_261
	global_load_dwordx2 v[96:97], v[100:101], off offset:288
	s_cbranch_execz .LBB0_262
	s_branch .LBB0_263

.LBB0_263:
	s_and_b64 vcc, exec, s[4:5]
	s_cbranch_vccnz .Lresid_f32_12
	s_waitcnt vmcnt(0)
	v_lshlrev_b32_e32 v70, 16, v72
	v_and_b32_e32 v71, 0xffff0000, v72
	v_lshlrev_b32_e32 v72, 16, v73
	v_and_b32_e32 v73, 0xffff0000, v73
	v_lshlrev_b32_e32 v78, 16, v80
	v_and_b32_e32 v79, 0xffff0000, v80
	v_lshlrev_b32_e32 v80, 16, v81
	v_and_b32_e32 v81, 0xffff0000, v81
	v_lshlrev_b32_e32 v86, 16, v88
	v_and_b32_e32 v87, 0xffff0000, v88
	v_lshlrev_b32_e32 v88, 16, v89
	v_and_b32_e32 v89, 0xffff0000, v89
	v_lshlrev_b32_e32 v94, 16, v96
	v_and_b32_e32 v95, 0xffff0000, v96
	v_lshlrev_b32_e32 v96, 16, v97
	v_and_b32_e32 v97, 0xffff0000, v97
.Lresid_f32_12:
	v_lshlrev_b64 v[98:99], 12, v[98:99]
	v_pk_add_f32 v[64:65], v[64:65], 0 op_sel_hi:[1,0]
	v_pk_add_f32 v[62:63], v[62:63], 0 op_sel_hi:[1,0]
	v_pk_add_f32 v[52:53], v[52:53], 0 op_sel_hi:[1,0]
	v_pk_add_f32 v[50:51], v[50:51], 0 op_sel_hi:[1,0]
	v_lshl_add_u64 v[98:99], s[22:23], 0, v[98:99]
	s_waitcnt vmcnt(3)
	v_pk_fma_f32 v[64:65], v[64:65], v[68:69], v[72:73]
	v_pk_fma_f32 v[62:63], v[62:63], v[66:67], v[70:71]
	v_pk_add_f32 v[56:57], v[56:57], 0 op_sel_hi:[1,0]
	v_pk_add_f32 v[54:55], v[54:55], 0 op_sel_hi:[1,0]
	s_waitcnt vmcnt(0)
	v_pk_fma_f32 v[52:53], v[52:53], v[92:93], v[96:97]
	v_pk_fma_f32 v[50:51], v[50:51], v[90:91], v[94:95]
	v_cvt_pk_bf16_f32 v62, v62, v63
	v_cvt_pk_bf16_f32 v63, v64, v65
	v_lshl_add_u64 v[64:65], v[162:163], 1, v[98:99]
	v_pk_fma_f32 v[56:57], v[56:57], v[76:77], v[80:81]
	v_pk_fma_f32 v[54:55], v[54:55], v[74:75], v[78:79]
	v_cvt_pk_bf16_f32 v50, v50, v51
	v_cvt_pk_bf16_f32 v51, v52, v53
	v_add_u32_e32 v0, 0xfffff090, v164
	v_cvt_pk_bf16_f32 v54, v54, v55
	v_cvt_pk_bf16_f32 v55, v56, v57
	global_store_dwordx2 v[64:65], v[50:51], off offset:288
	v_lshrrev_b32_e32 v50, 11, v0
	s_movk_i32 s0, 0xf70
	global_store_dwordx2 v[64:65], v[54:55], off offset:32
	v_pk_add_f32 v[54:55], v[60:61], 0 op_sel_hi:[1,0]
	v_pk_add_f32 v[56:57], v[58:59], 0 op_sel_hi:[1,0]
	v_add_u32_e32 v50, 1, v50
	v_cmp_gt_i32_e32 vcc, s0, v164
	v_pk_fma_f32 v[54:55], v[54:55], v[84:85], v[88:89]
	v_pk_fma_f32 v[56:57], v[56:57], v[82:83], v[86:87]
	v_cndmask_b32_e64 v52, v50, 0, vcc
	v_mov_b64_e32 v[50:51], s[6:7]
	v_cvt_pk_bf16_f32 v56, v56, v57
	v_cvt_pk_bf16_f32 v57, v54, v55
	v_mad_u64_u32 v[50:51], s[0:1], v52, s65, v[50:51]
	global_store_dwordx2 v[64:65], v[62:63], off
	global_store_dwordx2 v[64:65], v[56:57], off offset:256
	v_lshl_add_u64 v[74:75], v[162:163], 2, v[50:51]
	global_load_dwordx4 v[50:53], v[74:75], off
	v_add_u32_e32 v82, 0x90, v164
	v_ashrrev_i32_e32 v83, 31, v82
	v_cndmask_b32_e32 v54, v0, v82, vcc
	v_mov_b32_e32 v0, s64
	v_mov_b32_e32 v56, s96
	v_cndmask_b32_e32 v55, 0, v83, vcc
	v_cndmask_b32_e32 v57, v0, v56, vcc
	v_mov_b32_e32 v0, s62
	v_mov_b32_e32 v56, s66
	v_cndmask_b32_e32 v56, v0, v56, vcc
	v_lshlrev_b64 v[58:59], 12, v[54:55]
	v_lshl_add_u64 v[60:61], v[56:57], 0, v[58:59]
	s_mov_b64 s[0:1], -1
	s_and_b64 vcc, exec, s[4:5]
	v_lshl_add_u64 v[84:85], v[162:163], 1, v[60:61]
	s_cbranch_vccnz .LBB0_265
	global_load_dwordx2 v[56:57], v[84:85], off
	v_lshl_add_u64 v[58:59], v[60:61], 0, v[58:59]
	v_lshl_add_u64 v[86:87], v[162:163], 2, v[58:59]
	s_cbranch_execnz .LBB0_267
	s_branch .LBB0_266

.LBB0_267:
	global_load_dwordx4 v[58:61], v[74:75], off offset:64
	s_and_b64 vcc, exec, s[4:5]
	s_mov_b64 s[0:1], -1
	s_cbranch_vccnz .LBB0_269
	global_load_dwordx2 v[64:65], v[84:85], off offset:32
	s_cbranch_execnz .LBB0_271
	s_branch .LBB0_270

.LBB0_271:
	global_load_dwordx4 v[66:69], v[74:75], off offset:512
	s_and_b64 vcc, exec, s[4:5]
	s_mov_b64 s[0:1], -1
	s_cbranch_vccnz .LBB0_273
	global_load_dwordx2 v[72:73], v[84:85], off offset:256
	s_cbranch_execnz .LBB0_275
	s_branch .LBB0_274

.LBB0_275:
	s_nop 0
	global_load_dwordx4 v[74:77], v[74:75], off offset:576
	s_and_b64 vcc, exec, s[4:5]
	s_mov_b64 s[0:1], -1
	s_cbranch_vccnz .LBB0_277
	global_load_dwordx2 v[80:81], v[84:85], off offset:288
	s_cbranch_execz .LBB0_278
	s_branch .LBB0_279

.LBB0_279:
	s_and_b64 vcc, exec, s[4:5]
	s_cbranch_vccnz .Lresid_f32_13
	s_waitcnt vmcnt(0)
	v_lshlrev_b32_e32 v54, 16, v56
	v_and_b32_e32 v55, 0xffff0000, v56
	v_lshlrev_b32_e32 v56, 16, v57
	v_and_b32_e32 v57, 0xffff0000, v57
	v_lshlrev_b32_e32 v62, 16, v64
	v_and_b32_e32 v63, 0xffff0000, v64
	v_lshlrev_b32_e32 v64, 16, v65
	v_and_b32_e32 v65, 0xffff0000, v65
	v_lshlrev_b32_e32 v70, 16, v72
	v_and_b32_e32 v71, 0xffff0000, v72
	v_lshlrev_b32_e32 v72, 16, v73
	v_and_b32_e32 v73, 0xffff0000, v73
	v_lshlrev_b32_e32 v78, 16, v80
	v_and_b32_e32 v79, 0xffff0000, v80
	v_lshlrev_b32_e32 v80, 16, v81
	v_and_b32_e32 v81, 0xffff0000, v81
.Lresid_f32_13:
	v_lshlrev_b64 v[82:83], 12, v[82:83]
	v_pk_add_f32 v[48:49], v[48:49], 0 op_sel_hi:[1,0]
	v_pk_add_f32 v[46:47], v[46:47], 0 op_sel_hi:[1,0]
	v_pk_add_f32 v[36:37], v[36:37], 0 op_sel_hi:[1,0]
	v_pk_add_f32 v[34:35], v[34:35], 0 op_sel_hi:[1,0]
	v_lshl_add_u64 v[82:83], s[22:23], 0, v[82:83]
	s_waitcnt vmcnt(3)
	v_pk_fma_f32 v[48:49], v[48:49], v[52:53], v[56:57]
	v_pk_fma_f32 v[46:47], v[46:47], v[50:51], v[54:55]
	v_pk_add_f32 v[40:41], v[40:41], 0 op_sel_hi:[1,0]
	v_pk_add_f32 v[38:39], v[38:39], 0 op_sel_hi:[1,0]
	s_waitcnt vmcnt(0)
	v_pk_fma_f32 v[36:37], v[36:37], v[76:77], v[80:81]
	v_pk_fma_f32 v[34:35], v[34:35], v[74:75], v[78:79]
	v_cvt_pk_bf16_f32 v46, v46, v47
	v_cvt_pk_bf16_f32 v47, v48, v49
	v_lshl_add_u64 v[48:49], v[162:163], 1, v[82:83]
	v_pk_fma_f32 v[40:41], v[40:41], v[60:61], v[64:65]
	v_pk_fma_f32 v[38:39], v[38:39], v[58:59], v[62:63]
	v_cvt_pk_bf16_f32 v34, v34, v35
	v_cvt_pk_bf16_f32 v35, v36, v37
	v_add_u32_e32 v0, 0xfffff0a0, v164
	v_cvt_pk_bf16_f32 v38, v38, v39
	v_cvt_pk_bf16_f32 v39, v40, v41
	global_store_dwordx2 v[48:49], v[34:35], off offset:288
	v_lshrrev_b32_e32 v34, 11, v0
	s_movk_i32 s0, 0xf60
	global_store_dwordx2 v[48:49], v[38:39], off offset:32
	v_pk_add_f32 v[38:39], v[44:45], 0 op_sel_hi:[1,0]
	v_pk_add_f32 v[40:41], v[42:43], 0 op_sel_hi:[1,0]
	v_add_u32_e32 v34, 1, v34
	v_cmp_gt_i32_e32 vcc, s0, v164
	v_pk_fma_f32 v[38:39], v[38:39], v[68:69], v[72:73]
	v_pk_fma_f32 v[40:41], v[40:41], v[66:67], v[70:71]
	v_cndmask_b32_e64 v36, v34, 0, vcc
	v_mov_b64_e32 v[34:35], s[6:7]
	v_cvt_pk_bf16_f32 v40, v40, v41
	v_cvt_pk_bf16_f32 v41, v38, v39
	v_mad_u64_u32 v[34:35], s[0:1], v36, s65, v[34:35]
	global_store_dwordx2 v[48:49], v[46:47], off
	global_store_dwordx2 v[48:49], v[40:41], off offset:256
	v_lshl_add_u64 v[58:59], v[162:163], 2, v[34:35]
	global_load_dwordx4 v[34:37], v[58:59], off
	v_add_u32_e32 v66, 0xa0, v164
	v_ashrrev_i32_e32 v67, 31, v66
	v_cndmask_b32_e32 v38, v0, v66, vcc
	v_mov_b32_e32 v0, s64
	v_mov_b32_e32 v40, s96
	v_cndmask_b32_e32 v39, 0, v67, vcc
	v_cndmask_b32_e32 v41, v0, v40, vcc
	v_mov_b32_e32 v0, s62
	v_mov_b32_e32 v40, s66
	v_cndmask_b32_e32 v40, v0, v40, vcc
	v_lshlrev_b64 v[42:43], 12, v[38:39]
	v_lshl_add_u64 v[44:45], v[40:41], 0, v[42:43]
	s_mov_b64 s[0:1], -1
	s_and_b64 vcc, exec, s[4:5]
	v_lshl_add_u64 v[68:69], v[162:163], 1, v[44:45]
	s_cbranch_vccnz .LBB0_281
	global_load_dwordx2 v[40:41], v[68:69], off
	v_lshl_add_u64 v[42:43], v[44:45], 0, v[42:43]
	v_lshl_add_u64 v[70:71], v[162:163], 2, v[42:43]
	s_cbranch_execnz .LBB0_283
	s_branch .LBB0_282

.LBB0_283:
	global_load_dwordx4 v[42:45], v[58:59], off offset:64
	s_and_b64 vcc, exec, s[4:5]
	s_mov_b64 s[0:1], -1
	s_cbranch_vccnz .LBB0_285
	global_load_dwordx2 v[48:49], v[68:69], off offset:32
	s_cbranch_execnz .LBB0_287
	s_branch .LBB0_286

.LBB0_287:
	global_load_dwordx4 v[50:53], v[58:59], off offset:512
	s_and_b64 vcc, exec, s[4:5]
	s_mov_b64 s[0:1], -1
	s_cbranch_vccnz .LBB0_289
	global_load_dwordx2 v[56:57], v[68:69], off offset:256
	s_cbranch_execnz .LBB0_291
	s_branch .LBB0_290

.LBB0_291:
	s_nop 0
	global_load_dwordx4 v[58:61], v[58:59], off offset:576
	s_and_b64 vcc, exec, s[4:5]
	s_mov_b64 s[0:1], -1
	s_cbranch_vccnz .LBB0_293
	global_load_dwordx2 v[64:65], v[68:69], off offset:288
	s_cbranch_execz .LBB0_294
	s_branch .LBB0_295

.LBB0_295:
	s_and_b64 vcc, exec, s[4:5]
	s_cbranch_vccnz .Lresid_f32_14
	s_waitcnt vmcnt(0)
	v_lshlrev_b32_e32 v38, 16, v40
	v_and_b32_e32 v39, 0xffff0000, v40
	v_lshlrev_b32_e32 v40, 16, v41
	v_and_b32_e32 v41, 0xffff0000, v41
	v_lshlrev_b32_e32 v46, 16, v48
	v_and_b32_e32 v47, 0xffff0000, v48
	v_lshlrev_b32_e32 v48, 16, v49
	v_and_b32_e32 v49, 0xffff0000, v49
	v_lshlrev_b32_e32 v54, 16, v56
	v_and_b32_e32 v55, 0xffff0000, v56
	v_lshlrev_b32_e32 v56, 16, v57
	v_and_b32_e32 v57, 0xffff0000, v57
	v_lshlrev_b32_e32 v62, 16, v64
	v_and_b32_e32 v63, 0xffff0000, v64
	v_lshlrev_b32_e32 v64, 16, v65
	v_and_b32_e32 v65, 0xffff0000, v65
.Lresid_f32_14:
	v_lshlrev_b64 v[66:67], 12, v[66:67]
	v_pk_add_f32 v[32:33], v[32:33], 0 op_sel_hi:[1,0]
	v_pk_add_f32 v[30:31], v[30:31], 0 op_sel_hi:[1,0]
	v_pk_add_f32 v[20:21], v[20:21], 0 op_sel_hi:[1,0]
	v_pk_add_f32 v[18:19], v[18:19], 0 op_sel_hi:[1,0]
	v_lshl_add_u64 v[66:67], s[22:23], 0, v[66:67]
	s_waitcnt vmcnt(3)
	v_pk_fma_f32 v[32:33], v[32:33], v[36:37], v[40:41]
	v_pk_fma_f32 v[30:31], v[30:31], v[34:35], v[38:39]
	v_pk_add_f32 v[24:25], v[24:25], 0 op_sel_hi:[1,0]
	v_pk_add_f32 v[22:23], v[22:23], 0 op_sel_hi:[1,0]
	s_waitcnt vmcnt(0)
	v_pk_fma_f32 v[20:21], v[20:21], v[60:61], v[64:65]
	v_pk_fma_f32 v[18:19], v[18:19], v[58:59], v[62:63]
	v_cvt_pk_bf16_f32 v30, v30, v31
	v_cvt_pk_bf16_f32 v31, v32, v33
	v_lshl_add_u64 v[32:33], v[162:163], 1, v[66:67]
	v_pk_fma_f32 v[24:25], v[24:25], v[44:45], v[48:49]
	v_pk_fma_f32 v[22:23], v[22:23], v[42:43], v[46:47]
	v_cvt_pk_bf16_f32 v18, v18, v19
	v_cvt_pk_bf16_f32 v19, v20, v21
	v_add_u32_e32 v0, 0xfffff0b0, v164
	v_cvt_pk_bf16_f32 v22, v22, v23
	v_cvt_pk_bf16_f32 v23, v24, v25
	global_store_dwordx2 v[32:33], v[18:19], off offset:288
	v_lshrrev_b32_e32 v18, 11, v0
	s_movk_i32 s0, 0xf50
	global_store_dwordx2 v[32:33], v[22:23], off offset:32
	v_pk_add_f32 v[22:23], v[28:29], 0 op_sel_hi:[1,0]
	v_pk_add_f32 v[24:25], v[26:27], 0 op_sel_hi:[1,0]
	v_add_u32_e32 v18, 1, v18
	v_cmp_gt_i32_e32 vcc, s0, v164
	v_pk_fma_f32 v[22:23], v[22:23], v[52:53], v[56:57]
	v_pk_fma_f32 v[24:25], v[24:25], v[50:51], v[54:55]
	v_cndmask_b32_e64 v20, v18, 0, vcc
	v_mov_b64_e32 v[18:19], s[6:7]
	v_cvt_pk_bf16_f32 v24, v24, v25
	v_cvt_pk_bf16_f32 v25, v22, v23
	v_mad_u64_u32 v[18:19], s[0:1], v20, s65, v[18:19]
	global_store_dwordx2 v[32:33], v[30:31], off
	global_store_dwordx2 v[32:33], v[24:25], off offset:256
	v_lshl_add_u64 v[42:43], v[162:163], 2, v[18:19]
	global_load_dwordx4 v[18:21], v[42:43], off
	v_add_u32_e32 v50, 0xb0, v164
	v_ashrrev_i32_e32 v51, 31, v50
	v_cndmask_b32_e32 v22, v0, v50, vcc
	v_mov_b32_e32 v0, s64
	v_mov_b32_e32 v24, s96
	v_cndmask_b32_e32 v23, 0, v51, vcc
	v_cndmask_b32_e32 v25, v0, v24, vcc
	v_mov_b32_e32 v0, s62
	v_mov_b32_e32 v24, s66
	v_cndmask_b32_e32 v24, v0, v24, vcc
	v_lshlrev_b64 v[26:27], 12, v[22:23]
	v_lshl_add_u64 v[28:29], v[24:25], 0, v[26:27]
	s_mov_b64 s[0:1], -1
	s_and_b64 vcc, exec, s[4:5]
	v_lshl_add_u64 v[52:53], v[162:163], 1, v[28:29]
	s_cbranch_vccnz .LBB0_297
	global_load_dwordx2 v[24:25], v[52:53], off
	v_lshl_add_u64 v[26:27], v[28:29], 0, v[26:27]
	v_lshl_add_u64 v[54:55], v[162:163], 2, v[26:27]
	s_cbranch_execnz .LBB0_299
	s_branch .LBB0_298

.LBB0_299:
	global_load_dwordx4 v[26:29], v[42:43], off offset:64
	s_and_b64 vcc, exec, s[4:5]
	s_mov_b64 s[0:1], -1
	s_cbranch_vccnz .LBB0_301
	global_load_dwordx2 v[32:33], v[52:53], off offset:32
	s_cbranch_execnz .LBB0_303
	s_branch .LBB0_302

.LBB0_303:
	global_load_dwordx4 v[34:37], v[42:43], off offset:512
	s_and_b64 vcc, exec, s[4:5]
	s_mov_b64 s[0:1], -1
	s_cbranch_vccnz .LBB0_305
	global_load_dwordx2 v[40:41], v[52:53], off offset:256
	s_cbranch_execnz .LBB0_307
	s_branch .LBB0_306

.LBB0_307:
	s_nop 0
	global_load_dwordx4 v[42:45], v[42:43], off offset:576
	s_and_b64 vcc, exec, s[4:5]
	s_mov_b64 s[0:1], -1
	s_cbranch_vccnz .LBB0_309
	global_load_dwordx2 v[48:49], v[52:53], off offset:288
	s_cbranch_execnz .LBB0_176
	s_branch .LBB0_310
